# stack_i + nt cache policy on the global_load_dwordx4 tile loads of the M1 mixer units (ret_kv, lru, na)
# speedup vs baseline: 1.0014x; 1.0014x over previous
; #define LAS __attribute__((address_space(3)))
; __device__ __forceinline__ void ret_kv_unit(LAS unsigned char* lds, const bf16* P, bf16* KV, const float* dec, int u, int tid) {
;     asm volatile("" : "+v"(tid));
;     const int h = u & 3, n = u >> 2, lane = tid & 63, w = tid >> 6, g = lane >> 4, i = lane & 15;
;     const size_t t0 = (size_t)n * 128;
;     constexpr int RSK = 528, RSV = 272;
;     LAS unsigned char* Kt = lds; LAS unsigned char* Vf = lds + 67584; LAS unsigned char* Vb = Vf + 34816;
;     float dcf = dec[h], dcb = dec[4 + h];
;     u32x4 vva[4], vvb[4];
;     { u32x4 kq[8]; tile_load<128, 32>(kq, P + t0 * INC + C_RK + h * 256, INC, tid);
;       tile_load<128, 16>(vva, P + t0 * INC + C_RV + h * 256, INC, tid); tile_load<128, 16>(vvb, P + t0 * INC + C_RV + h * 256 + 128, INC, tid);
;       asm volatile("" : "+v"(dcf), "+v"(dcb));
;       tile_store<128, 32>(Kt, RSK, kq, tid); }
.LBB0_571:
	v_mbcnt_lo_u32_b32 v0, -1, 0
	v_mbcnt_hi_u32_b32 v0, -1, v0
	s_and_b32 s18, s9, 3
	v_add_u32_e32 v36, s59, v0
	s_ashr_i32 s12, s9, 2
	v_ashrrev_i32_e32 v10, 31, v36
	v_lshrrev_b32_e32 v0, 27, v10
	v_add_u32_e32 v0, v36, v0
	v_ashrrev_i32_e32 v37, 5, v0
	v_add_u32_e32 v40, 0x200, v36
	s_lshl_b32 s13, s18, 2
	s_mul_i32 s17, s12, 0x3c0000
	v_lshlrev_b32_e32 v0, 8, v37
	v_lshlrev_b32_e32 v11, 3, v36
	v_ashrrev_i32_e32 v12, 31, v40
	s_mul_hi_i32 s16, s12, 0x3c0000
	s_add_u32 s17, s0, s17
	v_sub_u32_e32 v6, v11, v0
	v_lshrrev_b32_e32 v0, 27, v12
	s_addc_u32 s19, s1, s16
	s_lshl_b32 s16, s18, 9
	v_add_u32_e32 v0, v40, v0
	s_add_u32 s16, s17, s16
	v_ashrrev_i32_e32 v38, 5, v0
	v_add_u32_e32 v39, 0x400, v36
	s_addc_u32 s17, s19, 0
	v_lshlrev_b32_e32 v0, 8, v38
	v_lshlrev_b32_e32 v13, 3, v40
	v_ashrrev_i32_e32 v14, 31, v39
	s_waitcnt lgkmcnt(0)
	v_mov_b64_e32 v[2:3], s[16:17]
	v_sub_u32_e32 v8, v13, v0
	v_lshrrev_b32_e32 v0, 27, v14
	v_mad_i64_i32 v[4:5], s[20:21], v37, s94, v[2:3]
	v_ashrrev_i32_e32 v7, 31, v6
	v_add_u32_e32 v0, v39, v0
	v_lshl_add_u64 v[4:5], v[6:7], 1, v[4:5]
	v_mad_i64_i32 v[6:7], s[20:21], v38, s94, v[2:3]
	v_ashrrev_i32_e32 v9, 31, v8
	v_ashrrev_i32_e32 v41, 5, v0
	v_add_u32_e32 v35, 0x600, v36
	v_lshl_add_u64 v[6:7], v[8:9], 1, v[6:7]
	v_lshlrev_b32_e32 v0, 8, v41
	v_lshlrev_b32_e32 v15, 3, v39
	v_ashrrev_i32_e32 v16, 31, v35
	global_load_dwordx4 v[42:45], v[4:5], off offset:2048 nt
	global_load_dwordx4 v[46:49], v[6:7], off offset:2048 nt
	v_sub_u32_e32 v6, v15, v0
	v_lshrrev_b32_e32 v0, 27, v16
	v_add_u32_e32 v0, v35, v0
	v_ashrrev_i32_e32 v74, 5, v0
	v_lshlrev_b32_e32 v0, 8, v74
	v_lshlrev_b32_e32 v17, 3, v35
	v_add_u32_e32 v75, 0x800, v36
	v_sub_u32_e32 v8, v17, v0
	v_ashrrev_i32_e32 v0, 31, v75
	v_mad_i64_i32 v[4:5], s[20:21], v41, s94, v[2:3]
	v_ashrrev_i32_e32 v7, 31, v6
	v_lshrrev_b32_e32 v0, 27, v0
	v_lshl_add_u64 v[4:5], v[6:7], 1, v[4:5]
	v_mad_i64_i32 v[6:7], s[20:21], v74, s94, v[2:3]
	v_ashrrev_i32_e32 v9, 31, v8
	v_add_u32_e32 v0, v75, v0
	v_lshl_add_u64 v[6:7], v[8:9], 1, v[6:7]
	v_ashrrev_i32_e32 v76, 5, v0
	global_load_dwordx4 v[50:53], v[4:5], off offset:2048 nt
	global_load_dwordx4 v[54:57], v[6:7], off offset:2048 nt
	v_lshlrev_b32_e32 v0, 8, v76
	v_lshlrev_b32_e32 v6, 3, v75
	v_add_u32_e32 v77, 0xa00, v36
	v_sub_u32_e32 v6, v6, v0
	v_ashrrev_i32_e32 v0, 31, v77
	v_lshrrev_b32_e32 v0, 27, v0
	v_add_u32_e32 v0, v77, v0
	v_ashrrev_i32_e32 v78, 5, v0
	v_lshlrev_b32_e32 v0, 8, v78
	v_lshlrev_b32_e32 v8, 3, v77
	v_add_u32_e32 v79, 0xc00, v36
	v_sub_u32_e32 v8, v8, v0
	v_ashrrev_i32_e32 v0, 31, v79
	v_mad_i64_i32 v[4:5], s[20:21], v76, s94, v[2:3]
	v_ashrrev_i32_e32 v7, 31, v6
	v_lshrrev_b32_e32 v0, 27, v0
	v_lshl_add_u64 v[4:5], v[6:7], 1, v[4:5]
	v_mad_i64_i32 v[6:7], s[20:21], v78, s94, v[2:3]
	v_ashrrev_i32_e32 v9, 31, v8
	v_add_u32_e32 v0, v79, v0
	v_lshl_add_u64 v[6:7], v[8:9], 1, v[6:7]
	v_ashrrev_i32_e32 v80, 5, v0
	global_load_dwordx4 v[58:61], v[4:5], off offset:2048 nt
	global_load_dwordx4 v[62:65], v[6:7], off offset:2048 nt
	v_lshlrev_b32_e32 v0, 8, v80
	v_lshlrev_b32_e32 v6, 3, v79
	v_add_u32_e32 v81, 0xe00, v36
	v_sub_u32_e32 v6, v6, v0
	v_ashrrev_i32_e32 v0, 31, v81
	v_lshrrev_b32_e32 v0, 27, v0
	v_add_u32_e32 v0, v81, v0
	v_mad_i64_i32 v[4:5], s[20:21], v80, s94, v[2:3]
	v_ashrrev_i32_e32 v7, 31, v6
	v_ashrrev_i32_e32 v82, 5, v0
	v_lshl_add_u64 v[4:5], v[6:7], 1, v[4:5]
	v_lshlrev_b32_e32 v6, 8, v82
	v_lshlrev_b32_e32 v7, 3, v81
	v_sub_u32_e32 v6, v7, v6
	v_mad_i64_i32 v[2:3], s[20:21], v82, s94, v[2:3]
	v_ashrrev_i32_e32 v7, 31, v6
	v_mov_b32_e32 v8, s13
	v_lshl_add_u64 v[2:3], v[6:7], 1, v[2:3]
	global_load_dword v0, v8, s[14:15] offset:16
	global_load_dword v34, v8, s[14:15]
	global_load_dwordx4 v[66:69], v[4:5], off offset:2048 nt
	global_load_dwordx4 v[70:73], v[2:3], off offset:2048 nt
	s_add_u32 s16, s16, 0x1000
	v_lshrrev_b32_e32 v2, 28, v10
	s_addc_u32 s17, s17, 0
	v_add_u32_e32 v2, v36, v2
	v_ashrrev_i32_e32 v6, 4, v2
	v_mov_b64_e32 v[2:3], s[16:17]
	v_mad_i64_i32 v[4:5], s[16:17], v6, s94, v[2:3]
	v_lshlrev_b32_e32 v6, 7, v6
	v_sub_u32_e32 v6, v11, v6
	v_ashrrev_i32_e32 v7, 31, v6
	v_lshl_add_u64 v[4:5], v[6:7], 1, v[4:5]
	v_lshrrev_b32_e32 v6, 28, v12
	v_add_u32_e32 v6, v40, v6
	v_ashrrev_i32_e32 v8, 4, v6
	v_mad_i64_i32 v[6:7], s[16:17], v8, s94, v[2:3]
	v_lshlrev_b32_e32 v8, 7, v8
	v_sub_u32_e32 v8, v13, v8
	v_ashrrev_i32_e32 v9, 31, v8
	v_lshl_add_u64 v[6:7], v[8:9], 1, v[6:7]
	v_lshrrev_b32_e32 v8, 28, v14
	v_add_u32_e32 v8, v39, v8
	v_ashrrev_i32_e32 v10, 4, v8
	v_mad_i64_i32 v[8:9], s[16:17], v10, s94, v[2:3]
	v_lshlrev_b32_e32 v10, 7, v10
	v_sub_u32_e32 v10, v15, v10
	v_ashrrev_i32_e32 v11, 31, v10
	v_lshl_add_u64 v[8:9], v[10:11], 1, v[8:9]
	v_lshrrev_b32_e32 v10, 28, v16
	v_add_u32_e32 v10, v35, v10
	v_ashrrev_i32_e32 v10, 4, v10
	v_mad_i64_i32 v[2:3], s[16:17], v10, s94, v[2:3]
	v_lshlrev_b32_e32 v10, 7, v10
	v_sub_u32_e32 v10, v17, v10
	v_ashrrev_i32_e32 v11, 31, v10
	v_lshl_add_u64 v[2:3], v[10:11], 1, v[2:3]
	global_load_dwordx4 v[30:33], v[4:5], off nt
	global_load_dwordx4 v[14:17], v[4:5], off offset:256 nt
	global_load_dwordx4 v[26:29], v[6:7], off nt
	global_load_dwordx4 v[10:13], v[6:7], off offset:256 nt
	global_load_dwordx4 v[22:25], v[8:9], off nt
	s_nop 0
	global_load_dwordx4 v[6:9], v[8:9], off offset:256 nt
	s_nop 0
	global_load_dwordx4 v[18:21], v[2:3], off nt
	s_nop 0
	global_load_dwordx4 v[2:5], v[2:3], off offset:256 nt
	v_mul_lo_u32 v83, v37, s55
	v_lshlrev_b32_e32 v84, 9, v37
	v_lshlrev_b32_e32 v37, 4, v36
	v_sub_u32_e32 v84, v37, v84
	v_add3_u32 v83, 0, v83, v84
	s_waitcnt vmcnt(0)
	ds_write_b128 v83, v[42:45]
	v_mul_lo_u32 v42, v38, s55
	v_lshlrev_b32_e32 v38, 9, v38
	v_lshlrev_b32_e32 v43, 4, v40
	v_sub_u32_e32 v38, v43, v38
	v_add3_u32 v38, 0, v42, v38
	ds_write_b128 v38, v[46:49]
	v_mul_lo_u32 v38, v41, s55
	v_lshlrev_b32_e32 v41, 9, v41
	v_lshlrev_b32_e32 v42, 4, v39
	v_sub_u32_e32 v41, v42, v41
	v_add3_u32 v38, 0, v38, v41
	v_lshlrev_b32_e32 v41, 9, v74
	v_lshlrev_b32_e32 v42, 4, v35
	ds_write_b128 v38, v[50:53]
	v_mul_lo_u32 v38, v74, s55
	v_sub_u32_e32 v41, v42, v41
	v_add3_u32 v38, 0, v38, v41
	v_lshlrev_b32_e32 v41, 9, v76
	v_lshlrev_b32_e32 v42, 4, v75
	ds_write_b128 v38, v[54:57]
	v_mul_lo_u32 v38, v76, s55
	v_sub_u32_e32 v41, v42, v41
	v_add3_u32 v38, 0, v38, v41
	v_lshlrev_b32_e32 v41, 9, v78
	v_lshlrev_b32_e32 v42, 4, v77
	ds_write_b128 v38, v[58:61]
	v_mul_lo_u32 v38, v78, s55
	v_sub_u32_e32 v41, v42, v41
	v_add3_u32 v38, 0, v38, v41
	v_lshlrev_b32_e32 v41, 9, v80
	v_lshlrev_b32_e32 v42, 4, v79
	ds_write_b128 v38, v[62:65]
	v_mul_lo_u32 v38, v80, s55
	v_sub_u32_e32 v41, v42, v41
	v_add3_u32 v38, 0, v38, v41
	v_mul_f32_e64 v41, |v34|, s30
	v_exp_f32_e32 v41, v41
	v_lshlrev_b32_e32 v42, 9, v82
	v_lshlrev_b32_e32 v43, 4, v81
	ds_write_b128 v38, v[66:69]
	v_mul_lo_u32 v38, v82, s55
	v_sub_u32_e32 v42, v43, v42
	v_add3_u32 v38, 0, v38, v42
	v_cmp_ngt_f32_e32 vcc, s8, v41
	ds_write_b128 v38, v[70:73]
	s_and_saveexec_b64 s[16:17], vcc
	s_xor_b64 s[16:17], exec, s[16:17]
	s_cbranch_execz .LBB0_573
; __device__ __forceinline__ float log1p_pos(float y) { const float z = y / (2.0f + y), z2 = z * z;
;     const float ser = 2.0f * z * (1.0f + z2 * (0.33333334f + z2 * (0.2f + z2 * (0.14285715f + z2 * 0.11111111f))));
;     return y < 0.25f ? ser : __logf(1.0f + y); }
; __device__ __forceinline__ float neg_expm1(float x) { const float p = -x * (1.0f + x * (0.5f + x * (0.16666667f + x * (0.041666668f + x * (0.008333334f + x * 0.0013888889f)))));
;     return x > -0.5f ? p : 1.0f - __expf(x); }
; __device__ __forceinline__ float softplus(float x) { return fmaxf(x, 0.f) + log1p_pos(__expf(-fabsf(x))); }
; __device__ __forceinline__ float log_sigmoid(float x) { return -softplus(-x); }
	v_add_f32_e32 v38, 1.0, v41
	v_cmp_gt_f32_e32 vcc, s96, v38
	s_nop 1
	v_cndmask_b32_e64 v41, 0, 32, vcc
	v_ldexp_f32 v38, v38, v41
	v_log_f32_e32 v38, v38
	s_nop 0
	v_mul_f32_e32 v41, 0x3f317217, v38
	v_fma_f32 v41, v38, s97, -v41
	v_fmac_f32_e32 v41, 0x3377d1cf, v38
	v_fmac_f32_e32 v41, 0x3f317217, v38
	v_cmp_lt_f32_e64 s[36:37], |v38|, s28
	s_nop 1
	v_cndmask_b32_e64 v38, v38, v41, s[36:37]
	v_cndmask_b32_e32 v41, 0, v231, vcc
	v_sub_f32_e32 v38, v38, v41

; #define LRU_XLOAD(uu) do { const int t0_ = 64 * ((uu) >> 3), c0_ = 128 * ((uu) & 7); _Pragma("unroll") for (int k = 0; k < 3; ++k) { const int idx = tid + k * NTHR, rr = idx >> 4, c8 = idx & 15, tok = t0_ - 2 + rr; \
;         xv[k] = (u32x4){0u, 0u, 0u, 0u}; if (idx < 67 * 16 && tok >= 0 && tok < SEQ) xv[k] = *(const u32x4*)(P + (size_t)tok * INC + C_LX + c0_ + c8 * 8); } } while (0)
; __device__ __forceinline__ void lru_units(LAS unsigned char* lds, const bf16* P, const bf16* LW, const float* wconv, const float* bconv, const float* ba, const float* bi, const float* lam,
;                                           float* LH, float* LSUM, int u0, int ustep, int nunits, int tid) {
;     ...
;     if (u0 < nunits) LRU_XLOAD(u0);
.LBB0_579:
	v_mbcnt_lo_u32_b32 v0, -1, 0
	v_mbcnt_hi_u32_b32 v0, -1, v0
	v_readlane_b32 s10, v253, 35
	v_add_u32_e32 v127, s59, v0
	v_readlane_b32 s11, v253, 36
	v_lshlrev_b32_e32 v0, 3, v127
	s_movk_i32 s9, 0x430
	s_and_b64 vcc, exec, s[10:11]
	v_ashrrev_i32_e32 v236, 4, v127
	v_cmp_gt_i32_e64 s[36:37], s9, v127
	v_and_b32_e32 v126, 0x78, v0
	s_cbranch_vccz .LBB0_587
	v_readlane_b32 s9, v253, 38
	s_waitcnt lgkmcnt(0)
	v_mov_b32_e32 v4, v1
	v_mov_b32_e32 v5, v1
	v_add_u32_e32 v0, s9, v236
	v_cmp_gt_u32_e32 vcc, s93, v0
	v_mov_b32_e32 v2, v1
	v_mov_b32_e32 v3, v1
	v_mov_b64_e32 v[8:9], v[4:5]
	s_and_b64 s[12:13], s[36:37], vcc
	v_lshlrev_b32_e32 v14, 1, v126
	v_mov_b64_e32 v[6:7], v[2:3]
	s_and_saveexec_b64 s[10:11], s[12:13]
	s_cbranch_execz .LBB0_582
	s_movk_i32 s9, 0x3c00
	v_mul_lo_u32 v0, v0, s9
	v_readlane_b32 s9, v253, 37
	v_lshl_add_u64 v[6:7], v[0:1], 1, s[0:1]
	s_lshl_b32 s26, s9, 1
	v_lshl_add_u64 v[6:7], v[6:7], 0, s[26:27]
	v_mov_b32_e32 v15, v1
	v_lshl_add_u64 v[6:7], v[6:7], 0, v[14:15]
	v_add_co_u32_e32 v6, vcc, 0x3000, v6
	s_nop 1
	v_addc_co_u32_e32 v7, vcc, 0, v7, vcc
	global_load_dwordx4 v[6:9], v[6:7], off offset:2048 nt
.LBB0_582:
	s_or_b64 exec, exec, s[10:11]
	v_add_u32_e32 v0, 0x200, v127
	v_ashrrev_i32_e32 v0, 4, v0
	v_readlane_b32 s9, v253, 38
	s_nop 1
	v_add_u32_e32 v0, s9, v0
	s_movk_i32 s9, 0x230
	v_cmp_gt_i32_e32 vcc, s9, v127
	v_cmp_gt_u32_e64 s[36:37], s93, v0
	s_and_b64 s[12:13], vcc, s[36:37]
	s_and_saveexec_b64 s[10:11], s[12:13]
	s_cbranch_execz .LBB0_584
	s_movk_i32 s9, 0x3c00
	v_mul_lo_u32 v0, v0, s9
	v_readlane_b32 s9, v253, 37
	v_lshl_add_u64 v[2:3], v[0:1], 1, s[0:1]
	s_lshl_b32 s26, s9, 1
	v_lshl_add_u64 v[2:3], v[2:3], 0, s[26:27]
	v_mov_b32_e32 v15, v1
	v_lshl_add_u64 v[2:3], v[2:3], 0, v[14:15]
	v_add_co_u32_e32 v2, vcc, 0x3000, v2
	s_nop 1
	v_addc_co_u32_e32 v3, vcc, 0, v3, vcc
	global_load_dwordx4 v[2:5], v[2:3], off offset:2048 nt
.LBB0_584:
	s_or_b64 exec, exec, s[10:11]
	v_add_u32_e32 v0, 0x400, v127
	v_ashrrev_i32_e32 v0, 4, v0
	v_readlane_b32 s9, v253, 38
	v_cmp_gt_i32_e32 vcc, 48, v127
	v_mov_b32_e32 v13, 0
	v_add_u32_e32 v0, s9, v0
	v_cmp_gt_u32_e64 s[36:37], s93, v0
	s_and_b64 s[12:13], vcc, s[36:37]
	v_mov_b32_e32 v12, 0
	v_mov_b32_e32 v11, 0
	v_mov_b32_e32 v10, 0
	s_and_saveexec_b64 s[10:11], s[12:13]
	s_cbranch_execz .LBB0_586
	s_movk_i32 s9, 0x3c00
	v_mul_lo_u32 v0, v0, s9
	v_readlane_b32 s9, v253, 37
	v_lshl_add_u64 v[10:11], v[0:1], 1, s[0:1]
	s_lshl_b32 s26, s9, 1
	v_lshl_add_u64 v[10:11], v[10:11], 0, s[26:27]
	v_mov_b32_e32 v15, v1
	v_lshl_add_u64 v[10:11], v[10:11], 0, v[14:15]
	v_add_co_u32_e32 v10, vcc, 0x3000, v10
	s_nop 1
	v_addc_co_u32_e32 v11, vcc, 0, v11, vcc
	global_load_dwordx4 v[10:13], v[10:11], off offset:2048 nt

; __device__ __forceinline__ void lru_units(LAS unsigned char* lds, const bf16* P, const bf16* LW, const float* wconv, const float* bconv, const float* ba, const float* bi, const float* lam,
;                                           float* LH, float* LSUM, int u0, int ustep, int nunits, int tid) {
;     ...
;         if (nb != nb_loaded) { const int nb_loaded_prev = nb_loaded; nb_loaded = nb;
; #pragma unroll
;             for (int ks = 0; ks < 4; ++ks) { const size_t o = (size_t)(16 * w + i) * 128 + 32 * ks + 8 * g;
;                 wa0[ks] = *(const bf16x8*)(LW + ((size_t)(0 * 2 + 0) * 8 + nb) * 16384 + o); wi0[ks] = *(const bf16x8*)(LW + ((size_t)(1 * 2 + 0) * 8 + nb) * 16384 + o);
;                 wa1[ks] = *(const bf16x8*)(LW + ((size_t)(0 * 2 + 1) * 8 + nb) * 16384 + o); wi1[ks] = *(const bf16x8*)(LW + ((size_t)(1 * 2 + 1) * 8 + nb) * 16384 + o); }
;             if (nb_loaded_prev >= 0) __syncthreads();
.LBB0_590:
	s_add_i32 s72, s2, s66
	s_and_b32 s73, s72, 7
	s_lshl_b32 s26, s73, 7
	s_cmp_eq_u32 s73, s71
	s_cbranch_scc1 .LBB0_604
	s_lshl_b32 s16, s73, 15
	s_add_u32 s16, s9, s16
	s_addc_u32 s17, s34, 0
	s_add_u32 s18, s16, 0x80000
	s_addc_u32 s19, s17, 0
	s_add_u32 s48, s16, 0x40000
	s_addc_u32 s49, s17, 0
	s_add_u32 s74, s16, 0xc0000
	s_addc_u32 s75, s17, 0
	v_lshl_add_u64 v[46:47], s[16:17], 0, v[130:131]
	v_lshl_add_u64 v[14:15], s[18:19], 0, v[130:131]
	v_lshl_add_u64 v[16:17], s[48:49], 0, v[130:131]
	v_lshl_add_u64 v[22:23], s[74:75], 0, v[130:131]
	v_lshl_add_u64 v[26:27], s[18:19], 0, v[132:133]
	global_load_dwordx4 v[18:21], v[14:15], off nt
	s_nop 0
	global_load_dwordx4 v[14:17], v[16:17], off nt
	s_nop 0
	global_load_dwordx4 v[30:33], v[46:47], off nt
	global_load_dwordx4 v[42:45], v[46:47], off offset:64 nt
	s_nop 0
	global_load_dwordx4 v[22:25], v[22:23], off nt
	s_nop 0
	global_load_dwordx4 v[38:41], v[26:27], off nt
	v_lshl_add_u64 v[26:27], s[48:49], 0, v[132:133]
	v_lshl_add_u64 v[28:29], s[74:75], 0, v[132:133]
	v_lshl_add_u64 v[48:49], s[18:19], 0, v[134:135]
	v_lshl_add_u64 v[50:51], s[48:49], 0, v[134:135]
	global_load_dwordx4 v[34:37], v[26:27], off nt
	s_nop 0
	global_load_dwordx4 v[26:29], v[28:29], off nt
	s_nop 0
	global_load_dwordx4 v[54:57], v[48:49], off nt
	s_nop 0
	global_load_dwordx4 v[50:53], v[50:51], off nt
	v_lshl_add_u64 v[48:49], s[74:75], 0, v[134:135]
	v_lshl_add_u64 v[58:59], s[18:19], 0, v[136:137]
	global_load_dwordx4 v[62:65], v[46:47], off offset:128 nt
	global_load_dwordx4 v[74:77], v[46:47], off offset:192 nt
	s_nop 0
	global_load_dwordx4 v[46:49], v[48:49], off nt
	s_nop 0
	global_load_dwordx4 v[70:73], v[58:59], off nt
	v_lshl_add_u64 v[58:59], s[48:49], 0, v[136:137]
	v_lshl_add_u64 v[60:61], s[74:75], 0, v[136:137]
	global_load_dwordx4 v[66:69], v[58:59], off nt
	s_nop 0
	global_load_dwordx4 v[58:61], v[60:61], off nt
	s_cmp_lt_i32 s71, 0
	s_cbranch_scc1 .LBB0_593
	s_waitcnt vmcnt(0)
	s_barrier

; #define LRU_XLOAD(uu) do { const int t0_ = 64 * ((uu) >> 3), c0_ = 128 * ((uu) & 7); _Pragma("unroll") for (int k = 0; k < 3; ++k) { const int idx = tid + k * NTHR, rr = idx >> 4, c8 = idx & 15, tok = t0_ - 2 + rr; \
;         xv[k] = (u32x4){0u, 0u, 0u, 0u}; if (idx < 67 * 16 && tok >= 0 && tok < SEQ) xv[k] = *(const u32x4*)(P + (size_t)tok * INC + C_LX + c0_ + c8 * 8); } } while (0)
; __device__ __forceinline__ void lru_units(LAS unsigned char* lds, const bf16* P, const bf16* LW, const float* wconv, const float* bconv, const float* ba, const float* bi, const float* lam,
;                                           float* LH, float* LSUM, int u0, int ustep, int nunits, int tid) {
;     ...
;         __syncthreads();
;         if (u + ustep < nunits) LRU_XLOAD(u + ustep);
.LBB0_610:
	s_add_i32 s16, s76, s66
	s_cmpk_lt_i32 s16, 0x400
	s_cselect_b64 s[48:49], -1, 0
	s_cmpk_gt_i32 s16, 0x3ff
	s_waitcnt vmcnt(0) lgkmcnt(0)
	s_barrier
	s_cbranch_scc1 .LBB0_618
	s_and_b32 s19, s68, 0xffffffc0
	s_add_i32 s19, s19, -2
	v_add_u32_e32 v0, s19, v236
	v_mov_b32_e32 v4, v1
	v_mov_b32_e32 v5, v1
	v_cmp_gt_u32_e32 vcc, s93, v0
	v_mov_b32_e32 v2, v1
	v_mov_b32_e32 v3, v1
	v_mov_b64_e32 v[8:9], v[4:5]
	s_and_b32 s18, s67, 0x380
	s_and_b64 s[74:75], s[42:43], vcc
	v_lshlrev_b32_e32 v78, 1, v126
	v_mov_b64_e32 v[6:7], v[2:3]
	s_and_saveexec_b64 s[16:17], s[74:75]
	s_cbranch_execz .LBB0_613
	s_movk_i32 s73, 0x3c00
	v_mul_lo_u32 v0, v0, s73
	v_lshl_add_u64 v[6:7], v[0:1], 1, s[0:1]
	s_lshl_b32 s74, s18, 1
	s_mov_b32 s75, s27
	v_lshl_add_u64 v[6:7], v[6:7], 0, s[74:75]
	v_mov_b32_e32 v79, v1
	v_lshl_add_u64 v[6:7], v[6:7], 0, v[78:79]
	v_add_co_u32_e32 v6, vcc, 0x3000, v6
	s_nop 1
	v_addc_co_u32_e32 v7, vcc, 0, v7, vcc
	global_load_dwordx4 v[6:9], v[6:7], off offset:2048 nt
.LBB0_613:
	s_or_b64 exec, exec, s[16:17]
	v_add_u32_e32 v0, s19, v250
	v_cmp_gt_u32_e32 vcc, s93, v0
	s_and_b64 s[74:75], s[44:45], vcc
	s_and_saveexec_b64 s[16:17], s[74:75]
	s_cbranch_execz .LBB0_615
	s_movk_i32 s73, 0x3c00
	v_mul_lo_u32 v0, v0, s73
	v_lshl_add_u64 v[2:3], v[0:1], 1, s[0:1]
	s_lshl_b32 s74, s18, 1
	s_mov_b32 s75, s27
	v_lshl_add_u64 v[2:3], v[2:3], 0, s[74:75]
	v_mov_b32_e32 v79, v1
	v_lshl_add_u64 v[2:3], v[2:3], 0, v[78:79]
	v_add_co_u32_e32 v2, vcc, 0x3000, v2
	s_nop 1
	v_addc_co_u32_e32 v3, vcc, 0, v3, vcc
	global_load_dwordx4 v[2:5], v[2:3], off offset:2048 nt
.LBB0_615:
	s_or_b64 exec, exec, s[16:17]
	v_add_u32_e32 v0, s19, v251
	v_cmp_gt_u32_e32 vcc, s93, v0
	s_and_b64 s[74:75], s[46:47], vcc
	v_mov_b32_e32 v13, 0
	v_mov_b32_e32 v12, 0
	v_mov_b32_e32 v11, 0
	v_mov_b32_e32 v10, 0
	s_and_saveexec_b64 s[16:17], s[74:75]
	s_cbranch_execz .LBB0_617
	s_movk_i32 s19, 0x3c00
	v_mul_lo_u32 v0, v0, s19
	v_lshl_add_u64 v[10:11], v[0:1], 1, s[0:1]
	s_lshl_b32 s18, s18, 1
	s_mov_b32 s19, s27
	v_lshl_add_u64 v[10:11], v[10:11], 0, s[18:19]
	v_mov_b32_e32 v79, v1
	v_lshl_add_u64 v[10:11], v[10:11], 0, v[78:79]
	v_add_co_u32_e32 v10, vcc, 0x3000, v10
	s_nop 1
	v_addc_co_u32_e32 v11, vcc, 0, v11, vcc
	global_load_dwordx4 v[10:13], v[10:11], off offset:2048 nt

; #define LAS __attribute__((address_space(3)))
; __device__ __forceinline__ void na_unit(LAS unsigned char* lds, const bf16* P, const float* rpb, bf16* BR, int u, int tid) {
;     asm volatile("" : "+v"(tid));
;     const int hd = u & 7, rp = u >> 3, lane = tid & 63, w = tid >> 6, half = w >> 2, j = w & 3, g = lane >> 4, i = lane & 15;
;     const int r = 2 * rp + half, rs0 = min(max(2 * rp - 4, 0), 120), rs1 = min(max(2 * rp - 3, 0), 120), d1 = rs1 - rs0, nu = 8 + d1;
;     const int rs = half ? rs1 : rs0, dh = half ? d1 : 0;
;     const int ks0 = j == 0 ? 0 : (j == 1 ? 8 : (j == 2 ? 24 : 32));
;     constexpr int RS = 272, RSP = 528, ROWB = 17408;
;     LAS unsigned char* Qt = lds; LAS unsigned char* KA = lds + 34816;
;     LAS unsigned char* Psc = lds + w * 8448; LAS unsigned char* VB = lds + 67584;
;     LAS float* rpbs = (LAS float*)(lds + 139264);
;     u32x4 qv[4], kv[18];
; #pragma unroll
;     for (int k = 0; k < 4; ++k) { const int idx = tid + k * NTHR, uu = idx >> 10, rr = (idx >> 4) & 63, c8 = idx & 15; qv[k] = *(const u32x4*)(P + ((size_t)(2 * rp + uu) * 64 + rr) * INC + C_NQ + hd * 128 + c8 * 8); }
; #pragma unroll
;     for (int k = 0; k < 18; ++k) { const int idx = tid + k * NTHR, uu = idx >> 10, rr = (idx >> 4) & 63, c8 = idx & 15; kv[k] = *(const u32x4*)(P + ((size_t)min(rs0 + uu, 127) * 64 + rr) * INC + C_NK + hd * 128 + c8 * 8); }
.LBB0_644:
	s_or_b64 exec, exec, s[12:13]
	s_ashr_i32 s9, s45, 2
	s_and_b32 s9, s9, -2
	v_ashrrev_i32_e32 v93, 10, v140
	s_waitcnt lgkmcnt(0)
	v_add_u32_e32 v2, s9, v93
	v_ashrrev_i32_e32 v3, 31, v2
	s_max_i32 s12, s9, 4
	v_bfe_u32 v94, v140, 4, 6
	v_lshlrev_b64 v[4:5], 6, v[2:3]
	s_add_i32 s12, s12, -4
	v_or_b32_e32 v4, v4, v94
	v_mov_b64_e32 v[2:3], s[0:1]
	s_and_b32 s19, s45, 7
	s_min_u32 s18, s12, 0x78
	v_mad_u64_u32 v[6:7], s[12:13], v4, s94, v[2:3]
	v_add_u32_e32 v141, 0x200, v140
	v_mad_i32_i24 v7, v5, s94, v7
	s_lshl_b32 s26, s19, 8
	v_ashrrev_i32_e32 v95, 10, v141
	v_lshl_add_u64 v[4:5], v[6:7], 0, s[26:27]
	v_add_u32_e32 v6, s9, v95
	v_ashrrev_i32_e32 v7, 31, v6
	v_lshlrev_b32_e32 v0, 3, v140
	v_bfe_u32 v96, v141, 4, 6
	v_lshlrev_b64 v[6:7], 6, v[6:7]
	v_and_b32_e32 v0, 0x78, v0
	v_or_b32_e32 v6, v6, v96
	v_lshlrev_b32_e32 v0, 1, v0
	v_mad_u64_u32 v[8:9], s[12:13], v6, s94, v[2:3]
	v_lshl_add_u64 v[4:5], v[4:5], 0, v[0:1]
	v_mad_i32_i24 v9, v7, s94, v9
	v_add_co_u32_e32 v4, vcc, s93, v4
	v_lshl_add_u64 v[6:7], v[8:9], 0, s[26:27]
	s_nop 0
	v_addc_co_u32_e32 v5, vcc, 0, v5, vcc
	v_lshl_add_u64 v[6:7], v[6:7], 0, v[0:1]
	v_add_co_u32_e32 v6, vcc, s93, v6
	s_nop 1
	v_addc_co_u32_e32 v7, vcc, 0, v7, vcc
	global_load_dwordx4 v[14:17], v[4:5], off nt
	global_load_dwordx4 v[10:13], v[6:7], off nt
	v_add_u32_e32 v4, 0x400, v140
	v_ashrrev_i32_e32 v97, 10, v4
	v_add_u32_e32 v4, s9, v97
	v_ashrrev_i32_e32 v5, 31, v4
	v_lshlrev_b64 v[4:5], 6, v[4:5]
	v_or_b32_e32 v4, v4, v94
	v_mad_u64_u32 v[6:7], s[12:13], v4, s94, v[2:3]
	v_mad_i32_i24 v7, v5, s94, v7
	v_lshl_add_u64 v[4:5], v[6:7], 0, s[26:27]
	v_add_u32_e32 v6, 0x600, v140
	v_ashrrev_i32_e32 v98, 10, v6
	v_bfe_u32 v99, v6, 4, 6
	v_add_u32_e32 v6, s9, v98
	v_ashrrev_i32_e32 v7, 31, v6
	v_lshlrev_b64 v[6:7], 6, v[6:7]
	v_or_b32_e32 v6, v6, v99
	v_mad_u64_u32 v[8:9], s[12:13], v6, s94, v[2:3]
	v_lshl_add_u64 v[4:5], v[4:5], 0, v[0:1]
	v_mad_i32_i24 v9, v7, s94, v9
	v_add_co_u32_e32 v4, vcc, s93, v4
	v_lshl_add_u64 v[6:7], v[8:9], 0, s[26:27]
	s_nop 0
	v_addc_co_u32_e32 v5, vcc, 0, v5, vcc
	v_lshl_add_u64 v[6:7], v[6:7], 0, v[0:1]
	v_add_co_u32_e32 v6, vcc, s93, v6
	s_nop 1
	v_addc_co_u32_e32 v7, vcc, 0, v7, vcc
	global_load_dwordx4 v[22:25], v[4:5], off nt
	global_load_dwordx4 v[18:21], v[6:7], off nt
	v_add_u32_e32 v4, s18, v93
	v_min_i32_e32 v4, 0x7f, v4
	v_ashrrev_i32_e32 v5, 31, v4
	v_add_u32_e32 v6, s18, v95
	v_lshlrev_b64 v[4:5], 6, v[4:5]
	v_min_i32_e32 v6, 0x7f, v6
	v_or_b32_e32 v4, v4, v94
	v_ashrrev_i32_e32 v7, 31, v6
	v_mad_u64_u32 v[142:143], s[12:13], v4, s94, v[2:3]
	v_lshlrev_b64 v[6:7], 6, v[6:7]
	v_mad_i32_i24 v143, v5, s94, v143
	v_or_b32_e32 v6, v6, v96
	v_lshl_add_u64 v[4:5], v[142:143], 0, s[26:27]
	v_mad_u64_u32 v[144:145], s[12:13], v6, s94, v[2:3]
	v_lshl_add_u64 v[4:5], v[4:5], 0, v[0:1]
	v_mad_i32_i24 v145, v7, s94, v145
	v_add_co_u32_e32 v4, vcc, s93, v4
	v_lshl_add_u64 v[6:7], v[144:145], 0, s[26:27]
	s_nop 0
	v_addc_co_u32_e32 v5, vcc, 0, v5, vcc
	v_lshl_add_u64 v[6:7], v[6:7], 0, v[0:1]
	v_add_co_u32_e32 v6, vcc, s93, v6
	s_nop 1
	v_addc_co_u32_e32 v7, vcc, 0, v7, vcc
	global_load_dwordx4 v[58:61], v[4:5], off offset:2048 nt
	global_load_dwordx4 v[62:65], v[6:7], off offset:2048 nt
	v_add_u32_e32 v4, s18, v97
	v_min_i32_e32 v4, 0x7f, v4
	v_ashrrev_i32_e32 v5, 31, v4
	v_add_u32_e32 v6, s18, v98
	v_lshlrev_b64 v[4:5], 6, v[4:5]
	v_min_i32_e32 v6, 0x7f, v6
	v_or_b32_e32 v4, v4, v94
	v_ashrrev_i32_e32 v7, 31, v6
	v_mad_u64_u32 v[146:147], s[12:13], v4, s94, v[2:3]
	v_lshlrev_b64 v[6:7], 6, v[6:7]
	v_mad_i32_i24 v147, v5, s94, v147
	v_or_b32_e32 v6, v6, v99
	v_lshl_add_u64 v[4:5], v[146:147], 0, s[26:27]
	v_mad_u64_u32 v[148:149], s[12:13], v6, s94, v[2:3]
	v_lshl_add_u64 v[4:5], v[4:5], 0, v[0:1]
	v_mad_i32_i24 v149, v7, s94, v149
	v_add_co_u32_e32 v4, vcc, s93, v4
	v_lshl_add_u64 v[6:7], v[148:149], 0, s[26:27]
	s_nop 0
	v_addc_co_u32_e32 v5, vcc, 0, v5, vcc
	v_lshl_add_u64 v[6:7], v[6:7], 0, v[0:1]
	v_add_co_u32_e32 v6, vcc, s93, v6
	s_nop 1
	v_addc_co_u32_e32 v7, vcc, 0, v7, vcc
	global_load_dwordx4 v[66:69], v[4:5], off offset:2048 nt
	global_load_dwordx4 v[70:73], v[6:7], off offset:2048 nt
	v_add_u32_e32 v4, 0x800, v140
	v_ashrrev_i32_e32 v100, 10, v4
	v_add_u32_e32 v4, s18, v100
	v_add_u32_e32 v6, 0xa00, v140
	v_min_i32_e32 v4, 0x7f, v4
	v_ashrrev_i32_e32 v101, 10, v6
	v_ashrrev_i32_e32 v5, 31, v4
	v_bfe_u32 v102, v6, 4, 6
	v_add_u32_e32 v6, s18, v101
	v_lshlrev_b64 v[4:5], 6, v[4:5]
	v_min_i32_e32 v6, 0x7f, v6
	v_or_b32_e32 v4, v4, v94
	v_ashrrev_i32_e32 v7, 31, v6
	v_mad_u64_u32 v[150:151], s[12:13], v4, s94, v[2:3]
	v_lshlrev_b64 v[6:7], 6, v[6:7]
	v_mad_i32_i24 v151, v5, s94, v151
	v_or_b32_e32 v6, v6, v102
	v_lshl_add_u64 v[4:5], v[150:151], 0, s[26:27]
	v_mad_u64_u32 v[152:153], s[12:13], v6, s94, v[2:3]
	v_lshl_add_u64 v[4:5], v[4:5], 0, v[0:1]
	v_mad_i32_i24 v153, v7, s94, v153
	v_add_co_u32_e32 v4, vcc, s93, v4
	v_lshl_add_u64 v[6:7], v[152:153], 0, s[26:27]
	s_nop 0
	v_addc_co_u32_e32 v5, vcc, 0, v5, vcc
	v_lshl_add_u64 v[6:7], v[6:7], 0, v[0:1]
	v_add_co_u32_e32 v6, vcc, s93, v6
	s_nop 1
	v_addc_co_u32_e32 v7, vcc, 0, v7, vcc
	global_load_dwordx4 v[78:81], v[4:5], off offset:2048 nt
	global_load_dwordx4 v[74:77], v[6:7], off offset:2048 nt
	v_add_u32_e32 v4, 0xc00, v140
	v_ashrrev_i32_e32 v103, 10, v4
	v_add_u32_e32 v4, s18, v103
	v_add_u32_e32 v6, 0xe00, v140
	v_min_i32_e32 v4, 0x7f, v4
	v_ashrrev_i32_e32 v104, 10, v6
	v_ashrrev_i32_e32 v5, 31, v4
	v_bfe_u32 v105, v6, 4, 6
	v_add_u32_e32 v6, s18, v104
	v_lshlrev_b64 v[4:5], 6, v[4:5]
	v_min_i32_e32 v6, 0x7f, v6
	v_or_b32_e32 v4, v4, v94
	v_ashrrev_i32_e32 v7, 31, v6
; __device__ __forceinline__ void na_unit(LAS unsigned char* lds, const bf16* P, const float* rpb, bf16* BR, int u, int tid) {
;     ...
;     for (int k = 0; k < 4; ++k) { const int idx = tid + k * NTHR, uu = idx >> 10, rr = (idx >> 4) & 63, c8 = idx & 15; qv[k] = *(const u32x4*)(P + ((size_t)(2 * rp + uu) * 64 + rr) * INC + C_NQ + hd * 128 + c8 * 8); }
; #pragma unroll
;     for (int k = 0; k < 18; ++k) { const int idx = tid + k * NTHR, uu = idx >> 10, rr = (idx >> 4) & 63, c8 = idx & 15; kv[k] = *(const u32x4*)(P + ((size_t)min(rs0 + uu, 127) * 64 + rr) * INC + C_NK + hd * 128 + c8 * 8); }
;     for (int idx = tid; idx < 465; idx += NTHR) rpbs[idx] = rpb[hd * 465 + idx] * 1.4426950408889634f;
	v_mad_u64_u32 v[154:155], s[12:13], v4, s94, v[2:3]
	v_lshlrev_b64 v[6:7], 6, v[6:7]
	v_mad_i32_i24 v155, v5, s94, v155
	v_or_b32_e32 v6, v6, v105
	v_lshl_add_u64 v[4:5], v[154:155], 0, s[26:27]
	v_mad_u64_u32 v[156:157], s[12:13], v6, s94, v[2:3]
	v_lshl_add_u64 v[4:5], v[4:5], 0, v[0:1]
	v_mad_i32_i24 v157, v7, s94, v157
	v_add_co_u32_e32 v4, vcc, s93, v4
	v_lshl_add_u64 v[6:7], v[156:157], 0, s[26:27]
	s_nop 0
	v_addc_co_u32_e32 v5, vcc, 0, v5, vcc
	v_lshl_add_u64 v[6:7], v[6:7], 0, v[0:1]
	v_add_co_u32_e32 v6, vcc, s93, v6
	s_nop 1
	v_addc_co_u32_e32 v7, vcc, 0, v7, vcc
	global_load_dwordx4 v[86:89], v[4:5], off offset:2048 nt
	global_load_dwordx4 v[82:85], v[6:7], off offset:2048 nt
	v_add_u32_e32 v4, 0x1000, v140
	v_ashrrev_i32_e32 v4, 10, v4
	v_add_u32_e32 v4, s18, v4
	v_add_u32_e32 v6, 0x1200, v140
	v_min_i32_e32 v4, 0x7f, v4
	v_ashrrev_i32_e32 v7, 10, v6
	v_ashrrev_i32_e32 v5, 31, v4
	v_lshrrev_b32_e32 v8, 4, v6
	v_add_u32_e32 v6, s18, v7
	v_lshlrev_b64 v[4:5], 6, v[4:5]
	v_min_i32_e32 v6, 0x7f, v6
	v_or_b32_e32 v4, v4, v94
	v_ashrrev_i32_e32 v7, 31, v6
	v_mad_u64_u32 v[158:159], s[12:13], v4, s94, v[2:3]
	v_lshlrev_b64 v[6:7], 6, v[6:7]
	v_mad_i32_i24 v159, v5, s94, v159
	v_and_or_b32 v6, v8, 63, v6
	v_lshl_add_u64 v[4:5], v[158:159], 0, s[26:27]
	v_mad_u64_u32 v[160:161], s[12:13], v6, s94, v[2:3]
	v_lshl_add_u64 v[4:5], v[4:5], 0, v[0:1]
	v_mad_i32_i24 v161, v7, s94, v161
	v_add_co_u32_e32 v4, vcc, s93, v4
	v_lshl_add_u64 v[6:7], v[160:161], 0, s[26:27]
	s_nop 0
	v_addc_co_u32_e32 v5, vcc, 0, v5, vcc
	v_lshl_add_u64 v[6:7], v[6:7], 0, v[0:1]
	v_add_co_u32_e32 v6, vcc, s93, v6
	s_nop 1
	v_addc_co_u32_e32 v7, vcc, 0, v7, vcc
	global_load_dwordx4 v[26:29], v[4:5], off offset:2048 nt
	global_load_dwordx4 v[30:33], v[6:7], off offset:2048 nt
	v_add_u32_e32 v4, 0x1400, v140
	v_ashrrev_i32_e32 v4, 10, v4
	v_add_u32_e32 v4, s18, v4
	v_add_u32_e32 v6, 0x1600, v140
	v_min_i32_e32 v4, 0x7f, v4
	v_ashrrev_i32_e32 v7, 10, v6
	v_ashrrev_i32_e32 v5, 31, v4
	v_lshrrev_b32_e32 v8, 4, v6
	v_add_u32_e32 v6, s18, v7
	v_lshlrev_b64 v[4:5], 6, v[4:5]
	v_min_i32_e32 v6, 0x7f, v6
	v_or_b32_e32 v4, v4, v94
	v_ashrrev_i32_e32 v7, 31, v6
	v_mad_u64_u32 v[162:163], s[12:13], v4, s94, v[2:3]
	v_lshlrev_b64 v[6:7], 6, v[6:7]
	v_mad_i32_i24 v163, v5, s94, v163
	v_and_or_b32 v6, v8, 63, v6
	v_lshl_add_u64 v[4:5], v[162:163], 0, s[26:27]
	v_mad_u64_u32 v[164:165], s[12:13], v6, s94, v[2:3]
	v_lshl_add_u64 v[4:5], v[4:5], 0, v[0:1]
	v_mad_i32_i24 v165, v7, s94, v165
	v_add_co_u32_e32 v4, vcc, s93, v4
	v_lshl_add_u64 v[6:7], v[164:165], 0, s[26:27]
	s_nop 0
	v_addc_co_u32_e32 v5, vcc, 0, v5, vcc
	v_lshl_add_u64 v[6:7], v[6:7], 0, v[0:1]
	v_add_co_u32_e32 v6, vcc, s93, v6
	s_nop 1
	v_addc_co_u32_e32 v7, vcc, 0, v7, vcc
	global_load_dwordx4 v[34:37], v[4:5], off offset:2048 nt
	global_load_dwordx4 v[38:41], v[6:7], off offset:2048 nt
	v_add_u32_e32 v4, 0x1800, v140
	v_ashrrev_i32_e32 v4, 10, v4
	v_add_u32_e32 v4, s18, v4
	v_add_u32_e32 v6, 0x1a00, v140
	v_min_i32_e32 v4, 0x7f, v4
	v_ashrrev_i32_e32 v7, 10, v6
	v_ashrrev_i32_e32 v5, 31, v4
	v_lshrrev_b32_e32 v8, 4, v6
	v_add_u32_e32 v6, s18, v7
	v_lshlrev_b64 v[4:5], 6, v[4:5]
	v_min_i32_e32 v6, 0x7f, v6
	v_or_b32_e32 v4, v4, v94
	v_ashrrev_i32_e32 v7, 31, v6
	v_mad_u64_u32 v[166:167], s[12:13], v4, s94, v[2:3]
	v_lshlrev_b64 v[6:7], 6, v[6:7]
	v_mad_i32_i24 v167, v5, s94, v167
	v_and_or_b32 v6, v8, 63, v6
	v_lshl_add_u64 v[4:5], v[166:167], 0, s[26:27]
	v_mad_u64_u32 v[168:169], s[12:13], v6, s94, v[2:3]
	v_lshl_add_u64 v[4:5], v[4:5], 0, v[0:1]
	v_mad_i32_i24 v169, v7, s94, v169
	v_add_co_u32_e32 v4, vcc, s93, v4
	v_lshl_add_u64 v[6:7], v[168:169], 0, s[26:27]
	s_nop 0
	v_addc_co_u32_e32 v5, vcc, 0, v5, vcc
	v_lshl_add_u64 v[6:7], v[6:7], 0, v[0:1]
	v_add_co_u32_e32 v6, vcc, s93, v6
	s_nop 1
	v_addc_co_u32_e32 v7, vcc, 0, v7, vcc
	global_load_dwordx4 v[42:45], v[4:5], off offset:2048 nt
	global_load_dwordx4 v[46:49], v[6:7], off offset:2048 nt
	v_add_u32_e32 v4, 0x1c00, v140
	v_ashrrev_i32_e32 v4, 10, v4
	v_add_u32_e32 v4, s18, v4
	v_add_u32_e32 v6, 0x1e00, v140
	v_min_i32_e32 v4, 0x7f, v4
	v_ashrrev_i32_e32 v7, 10, v6
	v_ashrrev_i32_e32 v5, 31, v4
	v_lshrrev_b32_e32 v8, 4, v6
	v_add_u32_e32 v6, s18, v7
	v_lshlrev_b64 v[4:5], 6, v[4:5]
	v_min_i32_e32 v6, 0x7f, v6
	v_or_b32_e32 v4, v4, v94
	v_ashrrev_i32_e32 v7, 31, v6
	v_mad_u64_u32 v[170:171], s[12:13], v4, s94, v[2:3]
	v_lshlrev_b64 v[6:7], 6, v[6:7]
	v_mad_i32_i24 v171, v5, s94, v171
	v_and_or_b32 v6, v8, 63, v6
	v_lshl_add_u64 v[4:5], v[170:171], 0, s[26:27]
	v_mad_u64_u32 v[172:173], s[12:13], v6, s94, v[2:3]
	v_lshl_add_u64 v[4:5], v[4:5], 0, v[0:1]
	v_mad_i32_i24 v173, v7, s94, v173
	v_add_co_u32_e32 v4, vcc, s93, v4
	v_lshl_add_u64 v[6:7], v[172:173], 0, s[26:27]
	s_nop 0
	v_addc_co_u32_e32 v5, vcc, 0, v5, vcc
	v_lshl_add_u64 v[6:7], v[6:7], 0, v[0:1]
	v_add_co_u32_e32 v6, vcc, s93, v6
	s_nop 1
	v_addc_co_u32_e32 v7, vcc, 0, v7, vcc
	global_load_dwordx4 v[50:53], v[4:5], off offset:2048 nt
	global_load_dwordx4 v[54:57], v[6:7], off offset:2048 nt
	v_add_u32_e32 v4, 0x2000, v140
	v_ashrrev_i32_e32 v4, 10, v4
	v_add_u32_e32 v4, s18, v4
	v_add_u32_e32 v6, 0x2200, v140
	v_min_i32_e32 v4, 0x7f, v4
	v_ashrrev_i32_e32 v7, 10, v6
	v_ashrrev_i32_e32 v5, 31, v4
	v_lshrrev_b32_e32 v8, 4, v6
	v_add_u32_e32 v6, s18, v7
	v_lshlrev_b64 v[4:5], 6, v[4:5]
	v_min_i32_e32 v6, 0x7f, v6
	v_or_b32_e32 v4, v4, v94
	v_ashrrev_i32_e32 v7, 31, v6
	v_mad_u64_u32 v[174:175], s[12:13], v4, s94, v[2:3]
	v_lshlrev_b64 v[6:7], 6, v[6:7]
	v_mad_i32_i24 v175, v5, s94, v175
	v_and_or_b32 v6, v8, 63, v6
	v_lshl_add_u64 v[4:5], v[174:175], 0, s[26:27]
	v_mad_u64_u32 v[176:177], s[12:13], v6, s94, v[2:3]
	v_lshl_add_u64 v[4:5], v[4:5], 0, v[0:1]
	v_mad_i32_i24 v177, v7, s94, v177
	v_add_co_u32_e32 v4, vcc, s93, v4
	v_lshl_add_u64 v[2:3], v[176:177], 0, s[26:27]
	s_nop 0
	v_addc_co_u32_e32 v5, vcc, 0, v5, vcc
	v_lshl_add_u64 v[2:3], v[2:3], 0, v[0:1]
	v_add_co_u32_e32 v6, vcc, 0x2000, v2
	s_movk_i32 s12, 0x1d1
	s_nop 0
	v_addc_co_u32_e32 v7, vcc, 0, v3, vcc
	global_load_dwordx4 v[2:5], v[4:5], off offset:2048 nt
	s_nop 0
	global_load_dwordx4 v[6:9], v[6:7], off offset:2048 nt
	v_cmp_gt_i32_e32 vcc, s12, v140
	s_and_saveexec_b64 s[12:13], vcc
	s_cbranch_execz .LBB0_652
	v_max_i32_e32 v90, 0xffffffd1, v140
	v_sub_u32_e32 v90, v90, v140
	v_add_u32_e32 v91, 0x1ff, v90
	s_movk_i32 s14, 0x1ff
	v_cmp_lt_u32_e32 vcc, s14, v91
	s_mov_b64 s[16:17], -1
	v_mov_b32_e32 v90, v140
	s_and_saveexec_b64 s[14:15], vcc
	s_cbranch_execz .LBB0_649
	v_lshrrev_b32_e32 v90, 9, v91
	v_add_u32_e32 v106, 1, v90
	s_mul_i32 s20, s19, 0x1d1
	v_and_b32_e32 v107, 0xfffffe, v106
	v_readlane_b32 s16, v254, 57
	s_mov_b32 s21, s20
	v_mov_b32_e32 v109, v107
	v_lshl_add_u32 v108, v140, 2, s16
	s_mov_b64 s[16:17], 0
	v_mov_b64_e32 v[90:91], v[140:141]

; __device__ __forceinline__ void na_unit(LAS unsigned char* lds, const bf16* P, const float* rpb, bf16* BR, int u, int tid) {
;     ...
;         __syncthreads();
;     }
;     u32x4 vv[18];
; #pragma unroll
;     for (int k = 0; k < 18; ++k) { const int idx = tid + k * NTHR, uu = idx >> 10, rr = (idx >> 4) & 63, c8 = idx & 15; vv[k] = *(const u32x4*)(P + ((size_t)min(rs0 + uu, 127) * 64 + rr) * INC + C_NV + hd * 128 + c8 * 8); }
;     const int cq = 16 * j + i, cst = min(max(cq - 8, 0), 48);
;     float mx = -1e30f;
; #pragma unroll
;     for (int kr = 0; kr < 8; ++kr)
; #pragma unroll
;         for (int mt = 0; mt < 2; ++mt)
; #pragma unroll
;             for (int q = 0; q < 4; ++q) { const int ck = ks0 + 16 * mt + 4 * g + q; const bool ok = ck >= cst && ck < cst + 16;
;                 const int dcl = min(max(ck - cq + 15, 0), 30);
;                 const float v = ok ? s[kr][mt][q] + rpbs[(rs + kr - r + 7) * 31 + dcl] : -1e30f; s[kr][mt][q] = v; mx = fmaxf(mx, v); }
.LBB0_686:
	s_or_b64 exec, exec, s[16:17]
	s_nop 3
	v_mov_b32_e32 v2, s20
	v_mov_b32_e32 v3, s18
	s_lshl_b32 s26, s19, 1
	v_cndmask_b32_e32 v200, v2, v3, vcc
	v_lshl_add_u64 v[2:3], v[142:143], 0, s[26:27]
	v_lshl_add_u64 v[2:3], v[2:3], 0, v[0:1]
	v_add_co_u32_e32 v2, vcc, s54, v2
	s_nop 1
	v_addc_co_u32_e32 v3, vcc, 0, v3, vcc
	s_barrier
	global_load_dwordx4 v[42:45], v[2:3], off nt
	v_lshl_add_u64 v[2:3], v[144:145], 0, s[26:27]
	v_lshl_add_u64 v[2:3], v[2:3], 0, v[0:1]
	v_add_co_u32_e32 v2, vcc, s54, v2
	v_lshl_add_u64 v[6:7], v[176:177], 0, s[26:27]
	s_nop 0
	v_addc_co_u32_e32 v3, vcc, 0, v3, vcc
	global_load_dwordx4 v[46:49], v[2:3], off nt
	v_lshl_add_u64 v[2:3], v[146:147], 0, s[26:27]
	v_lshl_add_u64 v[2:3], v[2:3], 0, v[0:1]
	v_add_co_u32_e32 v2, vcc, s54, v2
	v_lshl_add_u64 v[6:7], v[6:7], 0, v[0:1]
	s_nop 0
	v_addc_co_u32_e32 v3, vcc, 0, v3, vcc
	global_load_dwordx4 v[50:53], v[2:3], off nt
	v_lshl_add_u64 v[2:3], v[148:149], 0, s[26:27]
	v_lshl_add_u64 v[2:3], v[2:3], 0, v[0:1]
	v_add_co_u32_e32 v2, vcc, s54, v2
	v_bfe_u32 v195, v140, 4, 2
	s_nop 0
	v_addc_co_u32_e32 v3, vcc, 0, v3, vcc
	global_load_dwordx4 v[54:57], v[2:3], off nt
	v_lshl_add_u64 v[2:3], v[150:151], 0, s[26:27]
	v_lshl_add_u64 v[2:3], v[2:3], 0, v[0:1]
	v_add_co_u32_e32 v2, vcc, s54, v2
	v_add_u32_e32 v138, s9, v138
	s_nop 0
	v_addc_co_u32_e32 v3, vcc, 0, v3, vcc
	global_load_dwordx4 v[58:61], v[2:3], off nt
	v_lshl_add_u64 v[2:3], v[152:153], 0, s[26:27]
	v_lshl_add_u64 v[2:3], v[2:3], 0, v[0:1]
	v_add_co_u32_e32 v2, vcc, s54, v2
	v_sub_u32_e32 v142, v200, v138
	s_nop 0
	v_addc_co_u32_e32 v3, vcc, 0, v3, vcc
	global_load_dwordx4 v[62:65], v[2:3], off nt
	v_lshl_add_u64 v[2:3], v[154:155], 0, s[26:27]
	v_lshl_add_u64 v[2:3], v[2:3], 0, v[0:1]
	v_add_co_u32_e32 v2, vcc, s54, v2
	s_movk_i32 s9, 0x7c
	s_nop 0
	v_addc_co_u32_e32 v3, vcc, 0, v3, vcc
	global_load_dwordx4 v[66:69], v[2:3], off nt
	v_lshl_add_u64 v[2:3], v[156:157], 0, s[26:27]
	v_lshl_add_u64 v[2:3], v[2:3], 0, v[0:1]
	v_add_co_u32_e32 v2, vcc, s54, v2
	v_mul_lo_u32 v142, v142, s9
	s_nop 0
	v_addc_co_u32_e32 v3, vcc, 0, v3, vcc
	global_load_dwordx4 v[70:73], v[2:3], off nt
	v_lshl_add_u64 v[2:3], v[158:159], 0, s[26:27]
	v_lshl_add_u64 v[2:3], v[2:3], 0, v[0:1]
	v_add_co_u32_e32 v2, vcc, s54, v2
	v_readlane_b32 s9, v254, 58
	s_nop 0
	v_addc_co_u32_e32 v3, vcc, 0, v3, vcc
	global_load_dwordx4 v[10:13], v[2:3], off nt
	v_lshl_add_u64 v[2:3], v[160:161], 0, s[26:27]
	v_lshl_add_u64 v[2:3], v[2:3], 0, v[0:1]
	v_add_co_u32_e32 v2, vcc, s54, v2
	v_add_u32_e32 v144, s9, v142
	s_nop 0
	v_addc_co_u32_e32 v3, vcc, 0, v3, vcc
	global_load_dwordx4 v[14:17], v[2:3], off nt
	v_lshl_add_u64 v[2:3], v[162:163], 0, s[26:27]
	v_lshl_add_u64 v[2:3], v[2:3], 0, v[0:1]
	v_add_co_u32_e32 v2, vcc, s54, v2
	v_mov_b32_e32 v143, 0xf149f2ca
	s_nop 0
	v_addc_co_u32_e32 v3, vcc, 0, v3, vcc
	global_load_dwordx4 v[18:21], v[2:3], off nt
	v_lshl_add_u64 v[2:3], v[164:165], 0, s[26:27]
	v_lshl_add_u64 v[2:3], v[2:3], 0, v[0:1]
	v_add_co_u32_e32 v2, vcc, s54, v2
	s_nop 1
	v_addc_co_u32_e32 v3, vcc, 0, v3, vcc
	global_load_dwordx4 v[22:25], v[2:3], off nt
	v_lshl_add_u64 v[2:3], v[166:167], 0, s[26:27]
	v_lshl_add_u64 v[2:3], v[2:3], 0, v[0:1]
	v_add_co_u32_e32 v2, vcc, s54, v2
	s_nop 1
	v_addc_co_u32_e32 v3, vcc, 0, v3, vcc
	global_load_dwordx4 v[26:29], v[2:3], off nt
	v_lshl_add_u64 v[2:3], v[168:169], 0, s[26:27]
	v_lshl_add_u64 v[2:3], v[2:3], 0, v[0:1]
	v_add_co_u32_e32 v2, vcc, s54, v2
	s_nop 1
	v_addc_co_u32_e32 v3, vcc, 0, v3, vcc
	global_load_dwordx4 v[30:33], v[2:3], off nt
	v_lshl_add_u64 v[2:3], v[170:171], 0, s[26:27]
	v_lshl_add_u64 v[2:3], v[2:3], 0, v[0:1]
	v_add_co_u32_e32 v2, vcc, s54, v2
	s_nop 1
	v_addc_co_u32_e32 v3, vcc, 0, v3, vcc
	global_load_dwordx4 v[34:37], v[2:3], off nt
	v_lshl_add_u64 v[2:3], v[172:173], 0, s[26:27]
	v_lshl_add_u64 v[2:3], v[2:3], 0, v[0:1]
	v_add_co_u32_e32 v2, vcc, s54, v2
	s_nop 1
	v_addc_co_u32_e32 v3, vcc, 0, v3, vcc
	global_load_dwordx4 v[38:41], v[2:3], off nt
	v_lshl_add_u64 v[2:3], v[174:175], 0, s[26:27]
	v_lshl_add_u64 v[2:3], v[2:3], 0, v[0:1]
	v_add_co_u32_e32 v2, vcc, s54, v2
	v_sub_u32_e64 v0, v141, 8 clamp
	s_nop 0
	v_addc_co_u32_e32 v3, vcc, 0, v3, vcc
	v_add_co_u32_e32 v6, vcc, s54, v6
	global_load_dwordx4 v[2:5], v[2:3], off nt
	s_nop 0
	v_addc_co_u32_e32 v7, vcc, 0, v7, vcc
	global_load_dwordx4 v[6:9], v[6:7], off nt
	v_min_u32_e32 v152, 48, v0
	v_lshlrev_b32_e32 v0, 2, v195
	v_add_u32_e32 v154, v139, v0
	v_add_u32_e32 v153, 16, v152
	v_cmp_ge_u32_e32 vcc, v154, v152
	v_cmp_lt_u32_e64 s[36:37], v154, v153
	v_sub_u32_e32 v142, v154, v141
	s_and_b64 s[16:17], vcc, s[36:37]
	v_max_i32_e32 v145, -15, v142
	v_mov_b32_e32 v142, 0xf149f2ca
	s_and_saveexec_b64 s[18:19], s[16:17]
	s_cbranch_execz .LBB0_688
	v_add_u32_e32 v142, 15, v145
	v_min_u32_e32 v142, 30, v142
	v_lshl_add_u32 v142, v142, 2, v144
	ds_read_b32 v142, v142 offset:868
	s_waitcnt lgkmcnt(0)
	v_add_f32_e32 v142, v126, v142
